# v71 + first attention item's Q/gate rows warmed during the P2-P3 barrier + P2 k-norm and compress reductions via DPP
# speedup vs baseline: 1.0000x; 1.0000x over previous
.LBB0_448:
	s_waitcnt vmcnt(0)
	v_readlane_b32 s96, v249, 37
	v_readlane_b32 s97, v249, 38
	s_barrier
	v_readfirstlane_b32 s8, v202
	s_lshr_b32 s8, s8, 6
	s_cmp_lg_u32 s8, 4
	s_cbranch_scc1 .Lwpf_p3_end
	s_cmp_lg_u32 s86, 0x100
	s_cbranch_scc1 .Lwpf_p3_end
	v_readlane_b32 s9, v249, 46
	v_readlane_b32 s2, v249, 3
	v_readlane_b32 s3, v249, 4
	s_lshr_b32 s8, s9, 3
	s_and_b32 s9, s9, 7
	s_mul_hi_u32 s10, s8, 0xcccccccd
	s_lshr_b32 s10, s10, 2
	s_mul_i32 s11, s10, 5
	s_sub_i32 s11, s8, s11
	s_cmp_eq_u32 s11, 4
	s_cbranch_scc1 .Lwpf_p3_end
	s_lshl_b32 s10, s10, 2
	s_add_i32 s10, s10, s11
	s_sub_i32 s10, 63, s10
	s_lshl_b32 s9, s9, 12
	s_lshl_b32 s10, s10, 6
	s_add_i32 s9, s9, s10
	v_and_b32_e32 v0, 63, v202
	v_add_u32_e32 v0, s9, v0
	v_lshlrev_b32_e32 v2, 6, v0
	v_lshlrev_b32_e32 v0, 10, v0
	v_add_u32_e32 v0, 0x7000200, v0
	v_add_u32_e32 v2, 0x2b00000, v2
	global_load_dword v15, v0, s[2:3]
	global_load_dword v15, v0, s[2:3] offset:128
	global_load_dword v15, v0, s[2:3] offset:256
	global_load_dword v15, v0, s[2:3] offset:384
	global_load_dword v15, v2, s[2:3]
.Lwpf_p3_end:
	s_and_saveexec_b64 s[0:1], s[96:97]
	v_readlane_b32 s76, v249, 1
	v_readlane_b32 s66, v249, 44
	v_readlane_b32 s72, v249, 41
	v_readlane_b32 s82, v249, 21
	v_readlane_b32 s64, v249, 46
	v_readlane_b32 s77, v249, 2
	v_readlane_b32 s78, v249, 3
	v_readlane_b32 s79, v249, 4
	v_readlane_b32 s67, v249, 45
	v_readlane_b32 s65, v249, 43
	v_readlane_b32 s73, v249, 42
	s_mov_b64 s[88:89], s[86:87]
	v_readlane_b32 s83, v249, 22
	s_cbranch_execz .LBB0_500
	s_add_i32 s2, 0, 0x20160
	v_mov_b32_e32 v0, s2
	s_waitcnt vmcnt(0) expcnt(0) lgkmcnt(0)
	ds_read_b32 v2, v0
	s_add_i32 s2, 0, 0x20164
	v_mov_b32_e32 v0, s2
	ds_read_b32 v0, v0
	s_waitcnt lgkmcnt(1)
	v_cmp_ne_u32_e32 vcc, 0, v2
	s_cbranch_vccnz .LBB0_464
	v_readlane_b32 s2, v249, 0
	s_mul_i32 s33, s89, s2
	s_add_u32 s2, s78, 0x100200
	s_addc_u32 s3, s79, 0
	s_add_u32 s4, s78, 0x100400
	s_addc_u32 s5, s79, 0
	s_add_u32 s6, s78, 0x100500
	s_addc_u32 s7, s79, 0
	s_add_u32 s8, s78, 0x100600
	s_addc_u32 s9, s79, 0
	s_add_u32 s10, s78, 0x100700
	s_addc_u32 s11, s79, 0
	s_add_u32 s12, s78, 0x100800
	s_addc_u32 s13, s79, 0
	s_add_u32 s14, s78, 0x100900
	s_addc_u32 s15, s79, 0
	s_add_u32 s16, s78, 0x100a00
	s_addc_u32 s17, s79, 0
	s_add_u32 s18, s78, 0x100b00
	s_addc_u32 s19, s79, 0
	s_add_u32 s20, s78, 0x100c00
	s_addc_u32 s21, s79, 0
	s_add_u32 s22, s78, 0x100d00
	s_addc_u32 s23, s79, 0
	s_add_u32 s24, s78, 0x100e00
	s_addc_u32 s25, s79, 0
	s_add_u32 s26, s78, 0x100f00
	s_addc_u32 s27, s79, 0
	s_add_u32 s28, s78, 0x101000
	s_addc_u32 s29, s79, 0
	s_add_u32 s30, s78, 0x101100
	s_addc_u32 s31, s79, 0
	s_add_u32 s34, s78, 0x101200
	s_addc_u32 s35, s79, 0
	s_add_u32 s36, s78, 0x101300
	s_mul_i32 s33, s33, s88
	s_addc_u32 s37, s79, 0
	s_mov_b32 s44, 1
	v_mov_b32_e32 v16, 0
	s_branch .LBB0_452
